# heavy pool tasks (W=16/8): ring of 8 LDS row buffers read 8 ahead + v_dot2c_f32_bf16 window sums
# speedup vs baseline: 1.0035x; 1.0035x over previous
.LBB0_332:
	s_or_b64 exec, exec, s[6:7]
	s_waitcnt lgkmcnt(0)
	v_or_b32_e32 v2, s28, v1
	v_min_u32_e32 v3, 15, v2
	v_add_u32_e32 v3, 1, v3
	v_cvt_f32_ubyte0_e32 v3, v3
	v_div_scale_f32 v4, s[6:7], v3, v3, 1.0
	v_rcp_f32_e32 v5, v4
	s_ashr_i32 s8, s30, 6
	s_mul_i32 s10, s8, 15
	v_cmp_lt_u32_e64 s[6:7], s41, v2
	v_fma_f32 v6, -v4, v5, 1.0
	v_fmac_f32_e32 v5, v6, v5
	v_div_scale_f32 v6, vcc, 1.0, v3, 1.0
	v_mul_f32_e32 v7, v6, v5
	v_fma_f32 v8, -v4, v7, v6
	v_fmac_f32_e32 v7, v8, v5
	v_fma_f32 v4, -v4, v7, v6
	v_div_fmas_f32 v4, v4, v5, v7
	v_div_fixup_f32 v159, v4, v3, 1.0
	s_ashr_i32 s11, s10, 31
	v_add_u32_e32 v2, 0xfffff80f, v2
	v_mov_b32_e32 v3, v155
	v_lshl_add_u64 v[2:3], v[2:3], 0, s[10:11]
	v_lshlrev_b64 v[2:3], 11, v[2:3]
	v_lshl_add_u64 v[2:3], s[70:71], 0, v[2:3]
	v_mov_b32_e32 v163, v155
	v_lshl_add_u64 v[2:3], v[2:3], 0, v[162:163]
	v_lshl_add_u64 v[192:193], v[2:3], 0, s[16:17]
	v_mov_b32_e32 v2, 0
	s_mov_b32 s49, 0
	s_mov_b64 s[10:11], 0
	v_mov_b32_e32 v3, v2
	v_mov_b32_e32 v4, v2
	v_mov_b32_e32 v5, v2
	v_mov_b32_e32 v6, v2
	v_mov_b32_e32 v7, v2
	v_mov_b32_e32 v8, v2
	v_mov_b32_e32 v9, v2
	v_mov_b32_e32 v10, v2
	v_mov_b32_e32 v11, v2
	v_mov_b32_e32 v12, v2
	v_mov_b32_e32 v13, v2
	v_mov_b32_e32 v14, v2
	v_mov_b32_e32 v15, v2
	v_mov_b32_e32 v16, v2
	v_mov_b32_e32 v17, v2
	v_mov_b32_e32 v18, v2
	v_mov_b32_e32 v19, v2
	v_mov_b32_e32 v20, v2
	v_mov_b32_e32 v21, v2
	v_mov_b32_e32 v22, v2
	v_mov_b32_e32 v23, v2
	v_mov_b32_e32 v24, v2
	v_mov_b32_e32 v25, v2
	v_mov_b32_e32 v26, v2
	v_mov_b32_e32 v27, v2
	v_mov_b32_e32 v28, v2
	v_mov_b32_e32 v29, v2
	v_mov_b32_e32 v30, v2
	v_mov_b32_e32 v31, v2
	v_mov_b32_e32 v32, v2
	v_mov_b32_e32 v33, v2
	v_mov_b32_e32 v34, v2
	v_mov_b32_e32 v35, v2
	v_mov_b32_e32 v36, v2
	v_mov_b32_e32 v37, v2
	v_mov_b32_e32 v38, v2
	v_mov_b32_e32 v39, v2
	v_mov_b32_e32 v40, v2
	v_mov_b32_e32 v41, v2
	v_mov_b32_e32 v42, v2
	v_mov_b32_e32 v43, v2
	v_mov_b32_e32 v44, v2
	v_mov_b32_e32 v45, v2
	v_mov_b32_e32 v46, v2
	v_mov_b32_e32 v47, v2
	s_waitcnt vmcnt(3)
	v_mov_b64_e32 v[84:85], v[72:73]
	s_waitcnt vmcnt(2)
	v_mov_b64_e32 v[88:89], v[76:77]
	s_waitcnt vmcnt(1)
	v_mov_b64_e32 v[92:93], v[80:81]
	s_waitcnt vmcnt(0)
	v_mov_b64_e32 v[96:97], v[68:69]
	v_mov_b32_e32 v48, v2
	v_mov_b32_e32 v49, v2
	v_mov_b32_e32 v50, v2
	v_mov_b32_e32 v51, v2
	v_mov_b32_e32 v52, v2
	v_mov_b32_e32 v53, v2
	v_mov_b32_e32 v54, v2
	v_mov_b32_e32 v55, v2
	v_mov_b32_e32 v56, v2
	v_mov_b32_e32 v57, v2
	v_mov_b32_e32 v58, v2
	v_mov_b32_e32 v59, v2
	v_mov_b32_e32 v60, v2
	v_mov_b32_e32 v61, v2
	v_mov_b32_e32 v62, v2
	v_mov_b32_e32 v63, v2
	v_mov_b32_e32 v64, v2
	v_mov_b32_e32 v65, v2
	v_mov_b64_e32 v[82:83], v[70:71]
	v_mov_b64_e32 v[86:87], v[74:75]
	v_mov_b64_e32 v[90:91], v[78:79]
	v_mov_b64_e32 v[94:95], v[66:67]
	s_mov_b32 s50, 0x3f80
	s_mov_b32 s51, 0x3f800000
	v_lshl_add_u32 v163, v197, 1, v214
	ds_read_b128 v[222:225], v163 offset:4080
	ds_read_b128 v[226:229], v163 offset:3808
	ds_read_b128 v[230:233], v163 offset:3536
	ds_read_b128 v[234:237], v163 offset:3264
	ds_read_b128 v[238:241], v163 offset:2992
	ds_read_b128 v[242:245], v163 offset:2720
	ds_read_b128 v[248:251], v163 offset:2448
	ds_read_b128 v[252:255], v163 offset:2176
	s_cmpk_eq_i32 s10, 0xe0
	s_movk_i32 s8, 0x70
	s_cbranch_scc1 .LBB0_334

.LBB0_334:
	v_or_b32_e32 v98, s8, v197
	v_lshl_add_u32 v163, v98, 1, v214
	s_waitcnt lgkmcnt(7)
	v_lshlrev_b32_e32 v102, 16, v222
	v_and_b32_e32 v103, 0xffff0000, v222
	v_lshlrev_b32_e32 v104, 16, v223
	v_and_b32_e32 v105, 0xffff0000, v223
	v_lshlrev_b32_e32 v98, 16, v224
	v_and_b32_e32 v99, 0xffff0000, v224
	v_lshlrev_b32_e32 v100, 16, v225
	v_and_b32_e32 v101, 0xffff0000, v225
	v_mov_b64_e32 v[106:107], v[102:103]
	v_mov_b64_e32 v[108:109], v[104:105]
	v_mov_b64_e32 v[218:219], v[98:99]
	v_mov_b64_e32 v[220:221], v[100:101]
	ds_read_b128 v[222:225], v163 offset:1904
	s_waitcnt lgkmcnt(7)
	v_dot2c_f32_bf16 v106, s50, v226
	v_dot2c_f32_bf16 v107, s51, v226
	v_dot2c_f32_bf16 v108, s50, v227
	v_dot2c_f32_bf16 v109, s51, v227
	v_dot2c_f32_bf16 v218, s50, v228
	v_dot2c_f32_bf16 v219, s51, v228
	v_dot2c_f32_bf16 v220, s50, v229
	v_dot2c_f32_bf16 v221, s51, v229
	ds_read_b128 v[226:229], v163 offset:1632
	s_waitcnt lgkmcnt(7)
	v_dot2c_f32_bf16 v106, s50, v230
	v_dot2c_f32_bf16 v107, s51, v230
	v_dot2c_f32_bf16 v108, s50, v231
	v_dot2c_f32_bf16 v109, s51, v231
	v_dot2c_f32_bf16 v218, s50, v232
	v_dot2c_f32_bf16 v219, s51, v232
	v_dot2c_f32_bf16 v220, s50, v233
	v_dot2c_f32_bf16 v221, s51, v233
	ds_read_b128 v[230:233], v163 offset:1360
	s_waitcnt lgkmcnt(7)
	v_dot2c_f32_bf16 v106, s50, v234
	v_dot2c_f32_bf16 v107, s51, v234
	v_dot2c_f32_bf16 v108, s50, v235
	v_dot2c_f32_bf16 v109, s51, v235
	v_dot2c_f32_bf16 v218, s50, v236
	v_dot2c_f32_bf16 v219, s51, v236
	v_dot2c_f32_bf16 v220, s50, v237
	v_dot2c_f32_bf16 v221, s51, v237
	ds_read_b128 v[234:237], v163 offset:1088
	s_waitcnt lgkmcnt(7)
	v_dot2c_f32_bf16 v106, s50, v238
	v_dot2c_f32_bf16 v107, s51, v238
	v_dot2c_f32_bf16 v108, s50, v239
	v_dot2c_f32_bf16 v109, s51, v239
	v_dot2c_f32_bf16 v218, s50, v240
	v_dot2c_f32_bf16 v219, s51, v240
	v_dot2c_f32_bf16 v220, s50, v241
	v_dot2c_f32_bf16 v221, s51, v241
	ds_read_b128 v[238:241], v163 offset:816
	s_waitcnt lgkmcnt(7)
	v_dot2c_f32_bf16 v106, s50, v242
	v_dot2c_f32_bf16 v107, s51, v242
	v_dot2c_f32_bf16 v108, s50, v243
	v_dot2c_f32_bf16 v109, s51, v243
	v_dot2c_f32_bf16 v218, s50, v244
	v_dot2c_f32_bf16 v219, s51, v244
	v_dot2c_f32_bf16 v220, s50, v245
	v_dot2c_f32_bf16 v221, s51, v245
	ds_read_b128 v[242:245], v163 offset:544
	s_waitcnt lgkmcnt(7)
	v_dot2c_f32_bf16 v106, s50, v248
	v_dot2c_f32_bf16 v107, s51, v248
	v_dot2c_f32_bf16 v108, s50, v249
	v_dot2c_f32_bf16 v109, s51, v249
	v_dot2c_f32_bf16 v218, s50, v250
	v_dot2c_f32_bf16 v219, s51, v250
	v_dot2c_f32_bf16 v220, s50, v251
	v_dot2c_f32_bf16 v221, s51, v251
	ds_read_b128 v[248:251], v163 offset:272
	s_waitcnt lgkmcnt(7)
	v_dot2c_f32_bf16 v106, s50, v252
	v_dot2c_f32_bf16 v107, s51, v252
	v_dot2c_f32_bf16 v108, s50, v253
	v_dot2c_f32_bf16 v109, s51, v253
	v_dot2c_f32_bf16 v218, s50, v254
	v_dot2c_f32_bf16 v219, s51, v254
	v_dot2c_f32_bf16 v220, s50, v255
	v_dot2c_f32_bf16 v221, s51, v255
	ds_read_b128 v[252:255], v163
	s_waitcnt lgkmcnt(7)
	v_dot2c_f32_bf16 v106, s50, v222
	v_dot2c_f32_bf16 v107, s51, v222
	v_dot2c_f32_bf16 v108, s50, v223
	v_dot2c_f32_bf16 v109, s51, v223
	v_dot2c_f32_bf16 v218, s50, v224
	v_dot2c_f32_bf16 v219, s51, v224
	v_dot2c_f32_bf16 v220, s50, v225
	v_dot2c_f32_bf16 v221, s51, v225
	ds_read_b128 v[222:225], v163 offset:4112
	s_waitcnt lgkmcnt(7)
	v_dot2c_f32_bf16 v106, s50, v226
	v_dot2c_f32_bf16 v107, s51, v226
	v_dot2c_f32_bf16 v108, s50, v227
	v_dot2c_f32_bf16 v109, s51, v227
	v_dot2c_f32_bf16 v218, s50, v228
	v_dot2c_f32_bf16 v219, s51, v228
	v_dot2c_f32_bf16 v220, s50, v229
	v_dot2c_f32_bf16 v221, s51, v229
	ds_read_b128 v[226:229], v163 offset:3840
	s_waitcnt lgkmcnt(7)
	v_dot2c_f32_bf16 v106, s50, v230
	v_dot2c_f32_bf16 v107, s51, v230
	v_dot2c_f32_bf16 v108, s50, v231
	v_dot2c_f32_bf16 v109, s51, v231
	v_dot2c_f32_bf16 v218, s50, v232
	v_dot2c_f32_bf16 v219, s51, v232
	v_dot2c_f32_bf16 v220, s50, v233
	v_dot2c_f32_bf16 v221, s51, v233
	ds_read_b128 v[230:233], v163 offset:3568
	s_waitcnt lgkmcnt(7)
	v_dot2c_f32_bf16 v106, s50, v234
	v_dot2c_f32_bf16 v107, s51, v234
	v_dot2c_f32_bf16 v108, s50, v235
	v_dot2c_f32_bf16 v109, s51, v235
	v_dot2c_f32_bf16 v218, s50, v236
	v_dot2c_f32_bf16 v219, s51, v236
	v_dot2c_f32_bf16 v220, s50, v237
	v_dot2c_f32_bf16 v221, s51, v237
	ds_read_b128 v[234:237], v163 offset:3296
	s_waitcnt lgkmcnt(7)
	v_dot2c_f32_bf16 v106, s50, v238
	v_dot2c_f32_bf16 v107, s51, v238
	v_dot2c_f32_bf16 v108, s50, v239
	v_dot2c_f32_bf16 v109, s51, v239
	v_dot2c_f32_bf16 v218, s50, v240
	v_dot2c_f32_bf16 v219, s51, v240
	v_dot2c_f32_bf16 v220, s50, v241
	v_dot2c_f32_bf16 v221, s51, v241
	ds_read_b128 v[238:241], v163 offset:3024
	s_waitcnt lgkmcnt(7)
	v_dot2c_f32_bf16 v106, s50, v242
	v_dot2c_f32_bf16 v107, s51, v242
	v_dot2c_f32_bf16 v108, s50, v243
	v_dot2c_f32_bf16 v109, s51, v243
	v_dot2c_f32_bf16 v218, s50, v244
	v_dot2c_f32_bf16 v219, s51, v244
	v_dot2c_f32_bf16 v220, s50, v245
	v_dot2c_f32_bf16 v221, s51, v245
	ds_read_b128 v[242:245], v163 offset:2752
	s_waitcnt lgkmcnt(7)
	v_dot2c_f32_bf16 v106, s50, v248
	v_dot2c_f32_bf16 v107, s51, v248
	v_dot2c_f32_bf16 v108, s50, v249
	v_dot2c_f32_bf16 v109, s51, v249
	v_dot2c_f32_bf16 v218, s50, v250
	v_dot2c_f32_bf16 v219, s51, v250
	v_dot2c_f32_bf16 v220, s50, v251
	v_dot2c_f32_bf16 v221, s51, v251
	ds_read_b128 v[248:251], v163 offset:2480
	s_waitcnt lgkmcnt(7)
	v_dot2c_f32_bf16 v106, s50, v252
	v_dot2c_f32_bf16 v107, s51, v252
	v_dot2c_f32_bf16 v108, s50, v253
	v_dot2c_f32_bf16 v109, s51, v253
	v_dot2c_f32_bf16 v218, s50, v254
	v_dot2c_f32_bf16 v219, s51, v254
	v_dot2c_f32_bf16 v220, s50, v255
	v_dot2c_f32_bf16 v221, s51, v255
	ds_read_b128 v[252:255], v163 offset:2208
	v_fma_f32 v106, v159, v106, -v102
	v_fma_f32 v107, v159, v107, -v103
	v_fma_f32 v108, v159, v108, -v104
	v_fma_f32 v109, v159, v109, -v105
	v_fma_f32 v218, v159, v218, -v98
	v_fma_f32 v219, v159, v219, -v99
	v_fma_f32 v220, v159, v220, -v100
	v_fma_f32 v221, v159, v221, -v101
	v_cvt_pk_bf16_f32 v106, v106, v107
	v_cvt_pk_bf16_f32 v107, v108, v109
	v_cvt_pk_bf16_f32 v108, v218, v219
	v_cvt_pk_bf16_f32 v109, v220, v221
	s_and_saveexec_b64 s[28:29], s[6:7]
	s_cbranch_execz .LBB0_336
	v_lshl_add_u64 v[216:217], s[8:9], 2, v[192:193]
	global_store_dwordx4 v[216:217], v[102:105], off
	global_store_dwordx4 v[216:217], v[98:101], off offset:16

.LBB0_338:
	s_waitcnt lgkmcnt(0)
	v_or_b32_e32 v66, s48, v212
	v_ashrrev_i32_e32 v67, 31, v66
	v_lshlrev_b64 v[68:69], 11, v[66:67]
	v_cvt_pk_bf16_f32 v2, v2, v155
	v_lshl_add_u64 v[68:69], v[152:153], 0, v[68:69]
	v_or_b32_e32 v70, 2, v66
	global_store_short v[68:69], v2, off
	v_or_b32_e32 v2, 1, v66
	v_ashrrev_i32_e32 v71, 31, v70
	v_cvt_pk_bf16_f32 v67, v3, v155
	v_ashrrev_i32_e32 v3, 31, v2
	v_lshlrev_b64 v[70:71], 11, v[70:71]
	v_lshlrev_b64 v[2:3], 11, v[2:3]
	v_cvt_pk_bf16_f32 v4, v4, v155
	v_lshl_add_u64 v[70:71], v[152:153], 0, v[70:71]
	v_or_b32_e32 v72, 8, v66
	v_lshl_add_u64 v[2:3], v[152:153], 0, v[2:3]
	global_store_short v[70:71], v4, off
	v_or_b32_e32 v4, 3, v66
	v_ashrrev_i32_e32 v73, 31, v72
	global_store_short v[2:3], v67, off
	v_cvt_pk_bf16_f32 v67, v5, v155
	v_ashrrev_i32_e32 v5, 31, v4
	v_lshlrev_b64 v[72:73], 11, v[72:73]
	v_lshlrev_b64 v[4:5], 11, v[4:5]
	v_cvt_pk_bf16_f32 v6, v6, v155
	v_lshl_add_u64 v[72:73], v[152:153], 0, v[72:73]
	v_or_b32_e32 v74, 10, v66
	v_lshl_add_u64 v[4:5], v[152:153], 0, v[4:5]
	global_store_short v[72:73], v6, off
	v_or_b32_e32 v6, 9, v66
	v_ashrrev_i32_e32 v75, 31, v74
	global_store_short v[4:5], v67, off
	v_cvt_pk_bf16_f32 v67, v7, v155
	v_ashrrev_i32_e32 v7, 31, v6
	v_lshlrev_b64 v[74:75], 11, v[74:75]
	v_lshlrev_b64 v[6:7], 11, v[6:7]
	v_cvt_pk_bf16_f32 v8, v8, v155
	v_lshl_add_u64 v[74:75], v[152:153], 0, v[74:75]
	v_or_b32_e32 v76, 16, v66
	v_lshl_add_u64 v[6:7], v[152:153], 0, v[6:7]
	global_store_short v[74:75], v8, off
	v_or_b32_e32 v8, 11, v66
	v_ashrrev_i32_e32 v77, 31, v76
	v_cvt_pk_bf16_f32 v18, v18, v155
	global_store_short v[6:7], v67, off
	v_cvt_pk_bf16_f32 v67, v9, v155
	v_ashrrev_i32_e32 v9, 31, v8
	v_lshlrev_b64 v[76:77], 11, v[76:77]
	global_store_short v[68:69], v18, off offset:64
	v_cvt_pk_bf16_f32 v18, v19, v155
	v_lshlrev_b64 v[8:9], 11, v[8:9]
	v_cvt_pk_bf16_f32 v10, v10, v155
	v_lshl_add_u64 v[76:77], v[152:153], 0, v[76:77]
	v_or_b32_e32 v78, 18, v66
	global_store_short v[2:3], v18, off offset:64
	v_cvt_pk_bf16_f32 v18, v20, v155
	v_lshl_add_u64 v[8:9], v[152:153], 0, v[8:9]
	global_store_short v[76:77], v10, off
	v_or_b32_e32 v10, 17, v66
	v_ashrrev_i32_e32 v79, 31, v78
	global_store_short v[70:71], v18, off offset:64
	v_cvt_pk_bf16_f32 v18, v21, v155
	global_store_short v[8:9], v67, off
	v_cvt_pk_bf16_f32 v67, v11, v155
	v_ashrrev_i32_e32 v11, 31, v10
	v_lshlrev_b64 v[78:79], 11, v[78:79]
	global_store_short v[4:5], v18, off offset:64
	v_cvt_pk_bf16_f32 v18, v22, v155
	v_lshlrev_b64 v[10:11], 11, v[10:11]
	v_cvt_pk_bf16_f32 v12, v12, v155
	v_lshl_add_u64 v[78:79], v[152:153], 0, v[78:79]
	v_or_b32_e32 v80, 24, v66
	global_store_short v[72:73], v18, off offset:64
	v_cvt_pk_bf16_f32 v18, v23, v155
	v_lshl_add_u64 v[10:11], v[152:153], 0, v[10:11]
	global_store_short v[78:79], v12, off
	v_or_b32_e32 v12, 19, v66
	v_ashrrev_i32_e32 v81, 31, v80
	global_store_short v[6:7], v18, off offset:64
	v_cvt_pk_bf16_f32 v18, v24, v155
	global_store_short v[10:11], v67, off
	v_cvt_pk_bf16_f32 v67, v13, v155
	v_ashrrev_i32_e32 v13, 31, v12
	v_lshlrev_b64 v[80:81], 11, v[80:81]
	global_store_short v[74:75], v18, off offset:64
	v_cvt_pk_bf16_f32 v18, v25, v155
	v_lshlrev_b64 v[12:13], 11, v[12:13]
	v_cvt_pk_bf16_f32 v14, v14, v155
	v_lshl_add_u64 v[80:81], v[152:153], 0, v[80:81]
	s_waitcnt vmcnt(0)
	v_or_b32_e32 v82, 26, v66
	global_store_short v[8:9], v18, off offset:64
	v_cvt_pk_bf16_f32 v18, v26, v155
	v_lshl_add_u64 v[12:13], v[152:153], 0, v[12:13]
	global_store_short v[80:81], v14, off
	v_or_b32_e32 v14, 25, v66
	v_ashrrev_i32_e32 v83, 31, v82
	global_store_short v[76:77], v18, off offset:64
	v_cvt_pk_bf16_f32 v18, v27, v155
	global_store_short v[12:13], v67, off
	v_cvt_pk_bf16_f32 v67, v15, v155
	v_ashrrev_i32_e32 v15, 31, v14
	v_lshlrev_b64 v[82:83], 11, v[82:83]
	global_store_short v[10:11], v18, off offset:64
	v_cvt_pk_bf16_f32 v18, v28, v155
	v_lshlrev_b64 v[14:15], 11, v[14:15]
	v_cvt_pk_bf16_f32 v16, v16, v155
	v_lshl_add_u64 v[82:83], v[152:153], 0, v[82:83]
	global_store_short v[78:79], v18, off offset:64
	v_cvt_pk_bf16_f32 v18, v29, v155
	v_lshl_add_u64 v[14:15], v[152:153], 0, v[14:15]
	global_store_short v[82:83], v16, off
	v_or_b32_e32 v16, 27, v66
	global_store_short v[12:13], v18, off offset:64
	v_cvt_pk_bf16_f32 v18, v30, v155
	global_store_short v[14:15], v67, off
	v_cvt_pk_bf16_f32 v67, v17, v155
	v_ashrrev_i32_e32 v17, 31, v16
	global_store_short v[80:81], v18, off offset:64
	v_cvt_pk_bf16_f32 v18, v31, v155
	v_lshlrev_b64 v[16:17], 11, v[16:17]
	global_store_short v[14:15], v18, off offset:64
	v_cvt_pk_bf16_f32 v18, v32, v155
	v_lshl_add_u64 v[16:17], v[152:153], 0, v[16:17]
	global_store_short v[82:83], v18, off offset:64
	v_cvt_pk_bf16_f32 v18, v33, v155
	global_store_short v[16:17], v18, off offset:64
	v_cvt_pk_bf16_f32 v18, v34, v155
	global_store_short v[68:69], v18, off offset:128
	v_cvt_pk_bf16_f32 v18, v35, v155
	global_store_short v[2:3], v18, off offset:128
	v_cvt_pk_bf16_f32 v18, v36, v155
	global_store_short v[70:71], v18, off offset:128
	v_cvt_pk_bf16_f32 v18, v37, v155
	global_store_short v[4:5], v18, off offset:128
	v_cvt_pk_bf16_f32 v18, v38, v155
	global_store_short v[72:73], v18, off offset:128
	v_cvt_pk_bf16_f32 v18, v39, v155
	global_store_short v[6:7], v18, off offset:128
	v_cvt_pk_bf16_f32 v18, v40, v155
	global_store_short v[74:75], v18, off offset:128
	v_cvt_pk_bf16_f32 v18, v41, v155
	global_store_short v[8:9], v18, off offset:128
	v_cvt_pk_bf16_f32 v18, v42, v155
	global_store_short v[76:77], v18, off offset:128
	v_cvt_pk_bf16_f32 v18, v43, v155
	global_store_short v[10:11], v18, off offset:128
	v_cvt_pk_bf16_f32 v18, v44, v155
	global_store_short v[78:79], v18, off offset:128
	v_cvt_pk_bf16_f32 v18, v45, v155
	global_store_short v[12:13], v18, off offset:128
	v_cvt_pk_bf16_f32 v18, v46, v155
	global_store_short v[80:81], v18, off offset:128
	v_cvt_pk_bf16_f32 v18, v47, v155
	global_store_short v[14:15], v18, off offset:128
	v_cvt_pk_bf16_f32 v18, v48, v155
	global_store_short v[82:83], v18, off offset:128
	v_cvt_pk_bf16_f32 v18, v49, v155
	global_store_short v[16:17], v18, off offset:128
	v_cvt_pk_bf16_f32 v18, v50, v155
	global_store_short v[68:69], v18, off offset:192
	v_cvt_pk_bf16_f32 v18, v51, v155
	global_store_short v[2:3], v18, off offset:192
	v_cvt_pk_bf16_f32 v2, v52, v155
	global_store_short v[70:71], v2, off offset:192
	v_cvt_pk_bf16_f32 v2, v53, v155
	global_store_short v[4:5], v2, off offset:192
	v_cvt_pk_bf16_f32 v2, v54, v155
	global_store_short v[72:73], v2, off offset:192
	v_cvt_pk_bf16_f32 v2, v55, v155
	global_store_short v[6:7], v2, off offset:192
	v_cvt_pk_bf16_f32 v2, v56, v155
	global_store_short v[74:75], v2, off offset:192
	v_cvt_pk_bf16_f32 v2, v57, v155
	global_store_short v[8:9], v2, off offset:192
	v_cvt_pk_bf16_f32 v2, v58, v155
	global_store_short v[76:77], v2, off offset:192
	v_cvt_pk_bf16_f32 v2, v59, v155
	global_store_short v[10:11], v2, off offset:192
	v_cvt_pk_bf16_f32 v2, v60, v155
	global_store_short v[78:79], v2, off offset:192
	v_cvt_pk_bf16_f32 v2, v61, v155
	global_store_short v[12:13], v2, off offset:192
	v_cvt_pk_bf16_f32 v2, v62, v155
	global_store_short v[80:81], v2, off offset:192
	v_cvt_pk_bf16_f32 v2, v63, v155
	global_store_short v[14:15], v2, off offset:192
	v_cvt_pk_bf16_f32 v2, v64, v155
	global_store_short v[16:17], v67, off
	global_store_short v[82:83], v2, off offset:192
	v_cvt_pk_bf16_f32 v2, v65, v155
	global_store_short v[16:17], v2, off offset:192
	s_waitcnt lgkmcnt(0)
	s_mov_b64 s[6:7], 0

.LBB0_355:
	s_or_b64 exec, exec, s[6:7]
	s_waitcnt lgkmcnt(0)
	v_or_b32_e32 v2, s28, v1
	v_min_u32_e32 v3, 7, v2
	v_add_u32_e32 v3, 1, v3
	v_cvt_f32_ubyte0_e32 v3, v3
	v_div_scale_f32 v4, s[6:7], v3, v3, 1.0
	v_rcp_f32_e32 v5, v4
	s_ashr_i32 s8, s30, 6
	s_mul_i32 s10, s8, 15
	v_cmp_lt_u32_e64 s[6:7], s41, v2
	v_fma_f32 v6, -v4, v5, 1.0
	v_fmac_f32_e32 v5, v6, v5
	v_div_scale_f32 v6, vcc, 1.0, v3, 1.0
	v_mul_f32_e32 v7, v6, v5
	v_fma_f32 v8, -v4, v7, v6
	v_fmac_f32_e32 v7, v8, v5
	v_fma_f32 v4, -v4, v7, v6
	v_div_fmas_f32 v4, v4, v5, v7
	v_div_fixup_f32 v159, v4, v3, 1.0
	s_ashr_i32 s11, s10, 31
	v_add_u32_e32 v2, 0xfffff80f, v2
	v_mov_b32_e32 v3, v155
	v_lshl_add_u64 v[2:3], v[2:3], 0, s[10:11]
	v_lshlrev_b64 v[2:3], 11, v[2:3]
	v_lshl_add_u64 v[2:3], s[70:71], 0, v[2:3]
	v_mov_b32_e32 v163, v155
	v_lshl_add_u64 v[2:3], v[2:3], 0, v[162:163]
	v_lshl_add_u64 v[192:193], v[2:3], 0, s[20:21]
	v_mov_b32_e32 v2, 0
	s_mov_b32 s49, 0
	s_mov_b64 s[10:11], 0
	v_mov_b32_e32 v3, v2
	v_mov_b32_e32 v4, v2
	v_mov_b32_e32 v5, v2
	v_mov_b32_e32 v6, v2
	v_mov_b32_e32 v7, v2
	v_mov_b32_e32 v8, v2
	v_mov_b32_e32 v9, v2
	v_mov_b32_e32 v10, v2
	v_mov_b32_e32 v11, v2
	v_mov_b32_e32 v12, v2
	v_mov_b32_e32 v13, v2
	v_mov_b32_e32 v14, v2
	v_mov_b32_e32 v15, v2
	v_mov_b32_e32 v16, v2
	v_mov_b32_e32 v17, v2
	v_mov_b32_e32 v18, v2
	v_mov_b32_e32 v19, v2
	v_mov_b32_e32 v20, v2
	v_mov_b32_e32 v21, v2
	v_mov_b32_e32 v22, v2
	v_mov_b32_e32 v23, v2
	v_mov_b32_e32 v24, v2
	v_mov_b32_e32 v25, v2
	v_mov_b32_e32 v26, v2
	v_mov_b32_e32 v27, v2
	v_mov_b32_e32 v28, v2
	v_mov_b32_e32 v29, v2
	v_mov_b32_e32 v30, v2
	v_mov_b32_e32 v31, v2
	v_mov_b32_e32 v32, v2
	v_mov_b32_e32 v33, v2
	v_mov_b32_e32 v34, v2
	v_mov_b32_e32 v35, v2
	v_mov_b32_e32 v36, v2
	v_mov_b32_e32 v37, v2
	v_mov_b32_e32 v38, v2
	v_mov_b32_e32 v39, v2
	v_mov_b32_e32 v40, v2
	v_mov_b32_e32 v41, v2
	v_mov_b32_e32 v42, v2
	v_mov_b32_e32 v43, v2
	v_mov_b32_e32 v44, v2
	v_mov_b32_e32 v45, v2
	v_mov_b32_e32 v46, v2
	v_mov_b32_e32 v47, v2
	s_waitcnt vmcnt(3)
	v_mov_b64_e32 v[84:85], v[72:73]
	s_waitcnt vmcnt(2)
	v_mov_b64_e32 v[88:89], v[76:77]
	s_waitcnt vmcnt(1)
	v_mov_b64_e32 v[92:93], v[80:81]
	s_waitcnt vmcnt(0)
	v_mov_b64_e32 v[96:97], v[68:69]
	v_mov_b32_e32 v48, v2
	v_mov_b32_e32 v49, v2
	v_mov_b32_e32 v50, v2
	v_mov_b32_e32 v51, v2
	v_mov_b32_e32 v52, v2
	v_mov_b32_e32 v53, v2
	v_mov_b32_e32 v54, v2
	v_mov_b32_e32 v55, v2
	v_mov_b32_e32 v56, v2
	v_mov_b32_e32 v57, v2
	v_mov_b32_e32 v58, v2
	v_mov_b32_e32 v59, v2
	v_mov_b32_e32 v60, v2
	v_mov_b32_e32 v61, v2
	v_mov_b32_e32 v62, v2
	v_mov_b32_e32 v63, v2
	v_mov_b32_e32 v64, v2
	v_mov_b32_e32 v65, v2
	v_mov_b64_e32 v[82:83], v[70:71]
	v_mov_b64_e32 v[86:87], v[74:75]
	v_mov_b64_e32 v[90:91], v[78:79]
	v_mov_b64_e32 v[94:95], v[66:67]
	s_mov_b32 s50, 0x3f80
	s_mov_b32 s51, 0x3f800000
	v_lshl_add_u32 v163, v197, 1, v214
	ds_read_b128 v[222:225], v163 offset:4080
	ds_read_b128 v[226:229], v163 offset:3808
	ds_read_b128 v[230:233], v163 offset:3536
	ds_read_b128 v[234:237], v163 offset:3264
	ds_read_b128 v[238:241], v163 offset:2992
	ds_read_b128 v[242:245], v163 offset:2720
	ds_read_b128 v[248:251], v163 offset:2448
	ds_read_b128 v[252:255], v163 offset:2176
	s_cmpk_eq_i32 s10, 0xe0
	s_movk_i32 s8, 0x70
	s_cbranch_scc1 .LBB0_357

.LBB0_357:
	v_or_b32_e32 v98, s8, v197
	v_lshl_add_u32 v163, v98, 1, v214
	s_waitcnt lgkmcnt(7)
	v_lshlrev_b32_e32 v98, 16, v222
	v_and_b32_e32 v99, 0xffff0000, v222
	v_lshlrev_b32_e32 v100, 16, v223
	v_and_b32_e32 v101, 0xffff0000, v223
	v_lshlrev_b32_e32 v102, 16, v224
	v_and_b32_e32 v103, 0xffff0000, v224
	v_lshlrev_b32_e32 v104, 16, v225
	v_and_b32_e32 v105, 0xffff0000, v225
	v_mov_b64_e32 v[106:107], v[98:99]
	v_mov_b64_e32 v[108:109], v[100:101]
	v_mov_b64_e32 v[218:219], v[102:103]
	v_mov_b64_e32 v[220:221], v[104:105]
	ds_read_b128 v[222:225], v163 offset:4112
	s_waitcnt lgkmcnt(7)
	v_dot2c_f32_bf16 v106, s50, v226
	v_dot2c_f32_bf16 v107, s51, v226
	v_dot2c_f32_bf16 v108, s50, v227
	v_dot2c_f32_bf16 v109, s51, v227
	v_dot2c_f32_bf16 v218, s50, v228
	v_dot2c_f32_bf16 v219, s51, v228
	v_dot2c_f32_bf16 v220, s50, v229
	v_dot2c_f32_bf16 v221, s51, v229
	ds_read_b128 v[226:229], v163 offset:3840
	s_waitcnt lgkmcnt(7)
	v_dot2c_f32_bf16 v106, s50, v230
	v_dot2c_f32_bf16 v107, s51, v230
	v_dot2c_f32_bf16 v108, s50, v231
	v_dot2c_f32_bf16 v109, s51, v231
	v_dot2c_f32_bf16 v218, s50, v232
	v_dot2c_f32_bf16 v219, s51, v232
	v_dot2c_f32_bf16 v220, s50, v233
	v_dot2c_f32_bf16 v221, s51, v233
	ds_read_b128 v[230:233], v163 offset:3568
	s_waitcnt lgkmcnt(7)
	v_dot2c_f32_bf16 v106, s50, v234
	v_dot2c_f32_bf16 v107, s51, v234
	v_dot2c_f32_bf16 v108, s50, v235
	v_dot2c_f32_bf16 v109, s51, v235
	v_dot2c_f32_bf16 v218, s50, v236
	v_dot2c_f32_bf16 v219, s51, v236
	v_dot2c_f32_bf16 v220, s50, v237
	v_dot2c_f32_bf16 v221, s51, v237
	ds_read_b128 v[234:237], v163 offset:3296
	s_waitcnt lgkmcnt(7)
	v_dot2c_f32_bf16 v106, s50, v238
	v_dot2c_f32_bf16 v107, s51, v238
	v_dot2c_f32_bf16 v108, s50, v239
	v_dot2c_f32_bf16 v109, s51, v239
	v_dot2c_f32_bf16 v218, s50, v240
	v_dot2c_f32_bf16 v219, s51, v240
	v_dot2c_f32_bf16 v220, s50, v241
	v_dot2c_f32_bf16 v221, s51, v241
	ds_read_b128 v[238:241], v163 offset:3024
	s_waitcnt lgkmcnt(7)
	v_dot2c_f32_bf16 v106, s50, v242
	v_dot2c_f32_bf16 v107, s51, v242
	v_dot2c_f32_bf16 v108, s50, v243
	v_dot2c_f32_bf16 v109, s51, v243
	v_dot2c_f32_bf16 v218, s50, v244
	v_dot2c_f32_bf16 v219, s51, v244
	v_dot2c_f32_bf16 v220, s50, v245
	v_dot2c_f32_bf16 v221, s51, v245
	ds_read_b128 v[242:245], v163 offset:2752
	s_waitcnt lgkmcnt(7)
	v_dot2c_f32_bf16 v106, s50, v248
	v_dot2c_f32_bf16 v107, s51, v248
	v_dot2c_f32_bf16 v108, s50, v249
	v_dot2c_f32_bf16 v109, s51, v249
	v_dot2c_f32_bf16 v218, s50, v250
	v_dot2c_f32_bf16 v219, s51, v250
	v_dot2c_f32_bf16 v220, s50, v251
	v_dot2c_f32_bf16 v221, s51, v251
	ds_read_b128 v[248:251], v163 offset:2480
	s_waitcnt lgkmcnt(7)
	v_dot2c_f32_bf16 v106, s50, v252
	v_dot2c_f32_bf16 v107, s51, v252
	v_dot2c_f32_bf16 v108, s50, v253
	v_dot2c_f32_bf16 v109, s51, v253
	v_dot2c_f32_bf16 v218, s50, v254
	v_dot2c_f32_bf16 v219, s51, v254
	v_dot2c_f32_bf16 v220, s50, v255
	v_dot2c_f32_bf16 v221, s51, v255
	ds_read_b128 v[252:255], v163 offset:2208
	v_fma_f32 v106, v159, v106, -v98
	v_fma_f32 v107, v159, v107, -v99
	v_fma_f32 v108, v159, v108, -v100
	v_fma_f32 v109, v159, v109, -v101
	v_fma_f32 v218, v159, v218, -v102
	v_fma_f32 v219, v159, v219, -v103
	v_fma_f32 v220, v159, v220, -v104
	v_fma_f32 v221, v159, v221, -v105
	v_cvt_pk_bf16_f32 v106, v106, v107
	v_cvt_pk_bf16_f32 v107, v108, v109
	v_cvt_pk_bf16_f32 v108, v218, v219
	v_cvt_pk_bf16_f32 v109, v220, v221
	s_and_saveexec_b64 s[28:29], s[6:7]
	s_cbranch_execz .LBB0_359
	v_lshl_add_u64 v[216:217], s[8:9], 2, v[192:193]
	global_store_dwordx4 v[216:217], v[98:101], off
	global_store_dwordx4 v[216:217], v[102:105], off offset:16

.LBB0_361:
	s_waitcnt lgkmcnt(0)
	v_or_b32_e32 v66, s48, v212
	v_ashrrev_i32_e32 v67, 31, v66
	v_lshlrev_b64 v[68:69], 11, v[66:67]
	v_cvt_pk_bf16_f32 v2, v2, v155
	v_lshl_add_u64 v[68:69], v[120:121], 0, v[68:69]
	v_or_b32_e32 v70, 2, v66
	global_store_short v[68:69], v2, off
	v_or_b32_e32 v2, 1, v66
	v_ashrrev_i32_e32 v71, 31, v70
	v_cvt_pk_bf16_f32 v67, v3, v155
	v_ashrrev_i32_e32 v3, 31, v2
	v_lshlrev_b64 v[70:71], 11, v[70:71]
	v_lshlrev_b64 v[2:3], 11, v[2:3]
	v_cvt_pk_bf16_f32 v4, v4, v155
	v_lshl_add_u64 v[70:71], v[120:121], 0, v[70:71]
	v_or_b32_e32 v72, 8, v66
	v_lshl_add_u64 v[2:3], v[120:121], 0, v[2:3]
	global_store_short v[70:71], v4, off
	v_or_b32_e32 v4, 3, v66
	v_ashrrev_i32_e32 v73, 31, v72
	global_store_short v[2:3], v67, off
	v_cvt_pk_bf16_f32 v67, v5, v155
	v_ashrrev_i32_e32 v5, 31, v4
	v_lshlrev_b64 v[72:73], 11, v[72:73]
	v_lshlrev_b64 v[4:5], 11, v[4:5]
	v_cvt_pk_bf16_f32 v6, v6, v155
	v_lshl_add_u64 v[72:73], v[120:121], 0, v[72:73]
	v_or_b32_e32 v74, 10, v66
	v_lshl_add_u64 v[4:5], v[120:121], 0, v[4:5]
	global_store_short v[72:73], v6, off
	v_or_b32_e32 v6, 9, v66
	v_ashrrev_i32_e32 v75, 31, v74
	global_store_short v[4:5], v67, off
	v_cvt_pk_bf16_f32 v67, v7, v155
	v_ashrrev_i32_e32 v7, 31, v6
	v_lshlrev_b64 v[74:75], 11, v[74:75]
	v_lshlrev_b64 v[6:7], 11, v[6:7]
	v_cvt_pk_bf16_f32 v8, v8, v155
	v_lshl_add_u64 v[74:75], v[120:121], 0, v[74:75]
	v_or_b32_e32 v76, 16, v66
	v_lshl_add_u64 v[6:7], v[120:121], 0, v[6:7]
	global_store_short v[74:75], v8, off
	v_or_b32_e32 v8, 11, v66
	v_ashrrev_i32_e32 v77, 31, v76
	v_cvt_pk_bf16_f32 v18, v18, v155
	global_store_short v[6:7], v67, off
	v_cvt_pk_bf16_f32 v67, v9, v155
	v_ashrrev_i32_e32 v9, 31, v8
	v_lshlrev_b64 v[76:77], 11, v[76:77]
	global_store_short v[68:69], v18, off offset:64
	v_cvt_pk_bf16_f32 v18, v19, v155
	v_lshlrev_b64 v[8:9], 11, v[8:9]
	v_cvt_pk_bf16_f32 v10, v10, v155
	v_lshl_add_u64 v[76:77], v[120:121], 0, v[76:77]
	v_or_b32_e32 v78, 18, v66
	global_store_short v[2:3], v18, off offset:64
	v_cvt_pk_bf16_f32 v18, v20, v155
	v_lshl_add_u64 v[8:9], v[120:121], 0, v[8:9]
	global_store_short v[76:77], v10, off
	v_or_b32_e32 v10, 17, v66
	v_ashrrev_i32_e32 v79, 31, v78
	global_store_short v[70:71], v18, off offset:64
	v_cvt_pk_bf16_f32 v18, v21, v155
	global_store_short v[8:9], v67, off
	v_cvt_pk_bf16_f32 v67, v11, v155
	v_ashrrev_i32_e32 v11, 31, v10
	v_lshlrev_b64 v[78:79], 11, v[78:79]
	global_store_short v[4:5], v18, off offset:64
	v_cvt_pk_bf16_f32 v18, v22, v155
	v_lshlrev_b64 v[10:11], 11, v[10:11]
	v_cvt_pk_bf16_f32 v12, v12, v155
	v_lshl_add_u64 v[78:79], v[120:121], 0, v[78:79]
	v_or_b32_e32 v80, 24, v66
	global_store_short v[72:73], v18, off offset:64
	v_cvt_pk_bf16_f32 v18, v23, v155
	v_lshl_add_u64 v[10:11], v[120:121], 0, v[10:11]
	global_store_short v[78:79], v12, off
	v_or_b32_e32 v12, 19, v66
	v_ashrrev_i32_e32 v81, 31, v80
	global_store_short v[6:7], v18, off offset:64
	v_cvt_pk_bf16_f32 v18, v24, v155
	global_store_short v[10:11], v67, off
	v_cvt_pk_bf16_f32 v67, v13, v155
	v_ashrrev_i32_e32 v13, 31, v12
	v_lshlrev_b64 v[80:81], 11, v[80:81]
	global_store_short v[74:75], v18, off offset:64
	v_cvt_pk_bf16_f32 v18, v25, v155
	v_lshlrev_b64 v[12:13], 11, v[12:13]
	v_cvt_pk_bf16_f32 v14, v14, v155
	v_lshl_add_u64 v[80:81], v[120:121], 0, v[80:81]
	s_waitcnt vmcnt(0)
	v_or_b32_e32 v82, 26, v66
	global_store_short v[8:9], v18, off offset:64
	v_cvt_pk_bf16_f32 v18, v26, v155
	v_lshl_add_u64 v[12:13], v[120:121], 0, v[12:13]
	global_store_short v[80:81], v14, off
	v_or_b32_e32 v14, 25, v66
	v_ashrrev_i32_e32 v83, 31, v82
	global_store_short v[76:77], v18, off offset:64
	v_cvt_pk_bf16_f32 v18, v27, v155
	global_store_short v[12:13], v67, off
	v_cvt_pk_bf16_f32 v67, v15, v155
	v_ashrrev_i32_e32 v15, 31, v14
	v_lshlrev_b64 v[82:83], 11, v[82:83]
	global_store_short v[10:11], v18, off offset:64
	v_cvt_pk_bf16_f32 v18, v28, v155
	v_lshlrev_b64 v[14:15], 11, v[14:15]
	v_cvt_pk_bf16_f32 v16, v16, v155
	v_lshl_add_u64 v[82:83], v[120:121], 0, v[82:83]
	global_store_short v[78:79], v18, off offset:64
	v_cvt_pk_bf16_f32 v18, v29, v155
	v_lshl_add_u64 v[14:15], v[120:121], 0, v[14:15]
	global_store_short v[82:83], v16, off
	v_or_b32_e32 v16, 27, v66
	global_store_short v[12:13], v18, off offset:64
	v_cvt_pk_bf16_f32 v18, v30, v155
	global_store_short v[14:15], v67, off
	v_cvt_pk_bf16_f32 v67, v17, v155
	v_ashrrev_i32_e32 v17, 31, v16
	global_store_short v[80:81], v18, off offset:64
	v_cvt_pk_bf16_f32 v18, v31, v155
	v_lshlrev_b64 v[16:17], 11, v[16:17]
	global_store_short v[14:15], v18, off offset:64
	v_cvt_pk_bf16_f32 v18, v32, v155
	v_lshl_add_u64 v[16:17], v[120:121], 0, v[16:17]
	global_store_short v[82:83], v18, off offset:64
	v_cvt_pk_bf16_f32 v18, v33, v155
	global_store_short v[16:17], v18, off offset:64
	v_cvt_pk_bf16_f32 v18, v34, v155
	global_store_short v[68:69], v18, off offset:128
	v_cvt_pk_bf16_f32 v18, v35, v155
	global_store_short v[2:3], v18, off offset:128
	v_cvt_pk_bf16_f32 v18, v36, v155
	global_store_short v[70:71], v18, off offset:128
	v_cvt_pk_bf16_f32 v18, v37, v155
	global_store_short v[4:5], v18, off offset:128
	v_cvt_pk_bf16_f32 v18, v38, v155
	global_store_short v[72:73], v18, off offset:128
	v_cvt_pk_bf16_f32 v18, v39, v155
	global_store_short v[6:7], v18, off offset:128
	v_cvt_pk_bf16_f32 v18, v40, v155
	global_store_short v[74:75], v18, off offset:128
	v_cvt_pk_bf16_f32 v18, v41, v155
	global_store_short v[8:9], v18, off offset:128
	v_cvt_pk_bf16_f32 v18, v42, v155
	global_store_short v[76:77], v18, off offset:128
	v_cvt_pk_bf16_f32 v18, v43, v155
	global_store_short v[10:11], v18, off offset:128
	v_cvt_pk_bf16_f32 v18, v44, v155
	global_store_short v[78:79], v18, off offset:128
	v_cvt_pk_bf16_f32 v18, v45, v155
	global_store_short v[12:13], v18, off offset:128
	v_cvt_pk_bf16_f32 v18, v46, v155
	global_store_short v[80:81], v18, off offset:128
	v_cvt_pk_bf16_f32 v18, v47, v155
	global_store_short v[14:15], v18, off offset:128
	v_cvt_pk_bf16_f32 v18, v48, v155
	global_store_short v[82:83], v18, off offset:128
	v_cvt_pk_bf16_f32 v18, v49, v155
	global_store_short v[16:17], v18, off offset:128
	v_cvt_pk_bf16_f32 v18, v50, v155
	global_store_short v[68:69], v18, off offset:192
	v_cvt_pk_bf16_f32 v18, v51, v155
	global_store_short v[2:3], v18, off offset:192
	v_cvt_pk_bf16_f32 v2, v52, v155
	global_store_short v[70:71], v2, off offset:192
	v_cvt_pk_bf16_f32 v2, v53, v155
	global_store_short v[4:5], v2, off offset:192
	v_cvt_pk_bf16_f32 v2, v54, v155
	global_store_short v[72:73], v2, off offset:192
	v_cvt_pk_bf16_f32 v2, v55, v155
	global_store_short v[6:7], v2, off offset:192
	v_cvt_pk_bf16_f32 v2, v56, v155
	global_store_short v[74:75], v2, off offset:192
	v_cvt_pk_bf16_f32 v2, v57, v155
	global_store_short v[8:9], v2, off offset:192
	v_cvt_pk_bf16_f32 v2, v58, v155
	global_store_short v[76:77], v2, off offset:192
	v_cvt_pk_bf16_f32 v2, v59, v155
	global_store_short v[10:11], v2, off offset:192
	v_cvt_pk_bf16_f32 v2, v60, v155
	global_store_short v[78:79], v2, off offset:192
	v_cvt_pk_bf16_f32 v2, v61, v155
	global_store_short v[12:13], v2, off offset:192
	v_cvt_pk_bf16_f32 v2, v62, v155
	global_store_short v[80:81], v2, off offset:192
	v_cvt_pk_bf16_f32 v2, v63, v155
	global_store_short v[14:15], v2, off offset:192
	v_cvt_pk_bf16_f32 v2, v64, v155
	global_store_short v[16:17], v67, off
	global_store_short v[82:83], v2, off offset:192
	v_cvt_pk_bf16_f32 v2, v65, v155
	global_store_short v[16:17], v2, off offset:192
	s_waitcnt lgkmcnt(0)
